# MoBA near steps: one table base address with immediate offsets instead of 16 clamped per-element addresses; scale constant in SGPR, validity mask in VCC
# baseline (speedup 1.0000x reference)
; __device__ __forceinline__ float pair_max(float v) { auto r = __builtin_amdgcn_permlane32_swap(__float_as_uint(v), __float_as_uint(v), false, false); return fmaxf(__uint_as_float(r[0]), __uint_as_float(r[1])); }
; #define LDS_FENCE() asm volatile("" ::: "memory")
; template <int NS, int DT> __device__ __forceinline__ void softmax_upd(f32x16* s, float& m, float& l, f32x16* o) {
;     float mx = s[0][0];
; #pragma unroll
;     for (int i = 0; i < NS; ++i)
; #pragma unroll
;         for (int r = 0; r < 16; ++r) mx = fmaxf(mx, s[i][r]);
;     mx = pair_max(mx);
;     const bool grow = mx > m + 8.0f; const float mn = grow ? mx : m; float sum = 0.f;
;     if (__any(grow)) { const float alpha = __builtin_amdgcn_exp2f(m - mn); l *= alpha;
; #pragma unroll
;         for (int dt = 0; dt < DT; ++dt) o[dt] = o[dt] * alpha; }
; template <bool CAUSAL> __device__ __forceinline__ void moba_span(lbyte* kbuf, lbyte* vbuf, const bf16* Kh, const bf16* Vh, int kpos0, int nsub, const s16x8* qf, int tq, bool valid, int qlo, int qhi, ...
;     ...
;         } else {
;             float bb[16];
; #pragma unroll
;             for (int r = 0; r < 16; ++r) { int dist = tq - (key0 + kkrow(r, h)); dist = dist > 0 ? dist : 0; bb[r] = dtab[dist < MC_NDT - 1 ? dist : MC_NDT - 1]; }
;             LDS_FENCE();
; #pragma unroll
;             for (int r = 0; r < 16; ++r) { const int dist = tq - (key0 + kkrow(r, h)); const bool ok = valid && (!CAUSAL || dist >= 0); s[0][r] = ok ? s[0][r] * (0.125f * LOG2E) + bb[r] : -INFINITY; }
;             softmax_upd<1, 2>(s, m, l, o);
.LBB0_667:
	ds_read_b128 v[34:37], v252 offset:36864
	ds_read_b128 v[38:41], v252 offset:36896
	ds_read_b128 v[42:45], v252 offset:36928
	ds_read_b128 v[46:49], v252 offset:36960
	ds_read_b64_tr_b16 v[158:159], v253 offset:41472
	ds_read_b64_tr_b16 v[160:161], v253 offset:42048
	ds_read_b64_tr_b16 v[156:157], v253 offset:42112
	ds_read_b64_tr_b16 v[154:155], v253 offset:41536
	s_waitcnt lgkmcnt(7)
	v_mfma_f32_32x32x16_bf16 v[66:81], v[34:37], v[102:105], 0
	s_add_i32 s15, s14, s11
	s_sub_i32 s17, s15, 31
	s_max_i32 s23, s17, 16
	s_flbit_i32_b32 s24, s23
	s_lshl_b32 s24, s24, 1
	s_sub_i32 s26, 62, s24
	s_add_i32 s21, s15, 0xff
	s_max_i32 s15, s17, 0
	s_mul_i32 s23, s23, s23
	s_lshl_b32 s24, 2, s26
	s_waitcnt lgkmcnt(6)
	v_mfma_f32_32x32x16_bf16 v[66:81], v[38:41], v[110:113], v[66:81]
	s_cmp_ge_u32 s23, s24
	s_cselect_b32 s23, 1, 0
	ds_read_b64_tr_b16 v[150:151], v253 offset:43776
	ds_read_b64_tr_b16 v[152:153], v253 offset:44352
	ds_read_b64_tr_b16 v[148:149], v253 offset:44416
	ds_read_b64_tr_b16 v[146:147], v253 offset:43840
	s_or_b32 s23, s26, s23
	s_min_u32 s23, s23, 23
	s_add_i32 s23, s23, 8
	s_cmp_lt_i32 s17, 16
	s_waitcnt lgkmcnt(9)
	v_mfma_f32_32x32x16_bf16 v[66:81], v[42:45], v[114:117], v[66:81]
	s_cselect_b32 s15, s15, s23
	s_max_i32 s23, s21, 16
	s_flbit_i32_b32 s24, s23
	s_lshl_b32 s24, s24, 1
	s_sub_i32 s26, 62, s24
	s_max_i32 s17, s21, 0
	s_mul_i32 s23, s23, s23
	s_lshl_b32 s24, 2, s26
	s_cmp_ge_u32 s23, s24
	s_cselect_b32 s23, 1, 0
	s_waitcnt lgkmcnt(8)
	v_mfma_f32_32x32x16_bf16 v[66:81], v[46:49], v[118:121], v[66:81]
	s_or_b32 s23, s26, s23
	s_min_u32 s23, s23, 23
	s_add_i32 s23, s23, 8
	s_cmp_lt_i32 s21, 16
	s_cselect_b32 s17, s17, s23
	s_sub_i32 s21, s17, s15
	s_mov_b64 s[24:25], -1
	s_cmp_gt_i32 s21, 1
	v_add_f32_e32 v0, 0x41000000, v231
	s_cbranch_scc0 .LBB0_671
	s_mov_b64 vcc, s[8:9]
	s_mov_b32 s28, 0x3e38aa3b
	v_add_u32_e32 v34, s11, v237
	v_subrev_u32_e32 v34, 27, v34
	v_lshl_add_u32 v50, v34, 2, s82
	ds_read_b32 v35, v50 offset:108
	ds_read_b32 v36, v50 offset:104
	ds_read_b32 v37, v50 offset:100
	ds_read_b32 v38, v50 offset:96
	ds_read_b32 v39, v50 offset:76
	ds_read_b32 v40, v50 offset:72
	ds_read_b32 v41, v50 offset:68
	ds_read_b32 v42, v50 offset:64
	ds_read_b32 v43, v50 offset:44
	ds_read_b32 v44, v50 offset:40
	ds_read_b32 v45, v50 offset:36
	ds_read_b32 v46, v50 offset:32
	ds_read_b32 v47, v50 offset:12
	ds_read_b32 v48, v50 offset:8
	ds_read_b32 v49, v50 offset:4
	ds_read_b32 v34, v50
	s_waitcnt lgkmcnt(14)
	v_fmac_f32_e32 v35, s28, v66
	v_fmac_f32_e32 v36, s28, v67
	v_cndmask_b32_e32 v82, v238, v35, vcc
	v_cndmask_b32_e32 v83, v238, v36, vcc
	s_waitcnt lgkmcnt(13)
	v_fmac_f32_e32 v37, s28, v68
	s_waitcnt lgkmcnt(12)
	v_fmac_f32_e32 v38, s28, v69
	s_waitcnt lgkmcnt(0)
	v_fmac_f32_e32 v34, s28, v81
	v_cndmask_b32_e32 v84, v238, v37, vcc
	v_cndmask_b32_e32 v85, v238, v38, vcc
	v_fmac_f32_e32 v39, s28, v70
	v_fmac_f32_e32 v40, s28, v71
	v_cndmask_b32_e32 v97, v238, v34, vcc
	v_max_f32_e32 v34, v82, v83
	v_cndmask_b32_e32 v86, v238, v39, vcc
	v_cndmask_b32_e32 v87, v238, v40, vcc
	v_fmac_f32_e32 v41, s28, v72
	v_fmac_f32_e32 v42, s28, v73
	v_max3_f32 v34, v34, v84, v85
	v_cndmask_b32_e32 v88, v238, v41, vcc
	v_cndmask_b32_e32 v89, v238, v42, vcc
	v_fmac_f32_e32 v43, s28, v74
	v_fmac_f32_e32 v44, s28, v75
	v_max3_f32 v34, v34, v86, v87
	v_cndmask_b32_e32 v90, v238, v43, vcc
	v_cndmask_b32_e32 v91, v238, v44, vcc
	v_fmac_f32_e32 v45, s28, v76
	v_fmac_f32_e32 v46, s28, v77
	v_max3_f32 v34, v34, v88, v89
	v_cndmask_b32_e32 v92, v238, v45, vcc
	v_cndmask_b32_e32 v93, v238, v46, vcc
	v_fmac_f32_e32 v47, s28, v78
	v_fmac_f32_e32 v48, s28, v79
	v_max3_f32 v34, v34, v90, v91
	v_cndmask_b32_e32 v94, v238, v47, vcc
	v_cndmask_b32_e32 v95, v238, v48, vcc
	v_fmac_f32_e32 v49, s28, v80
	v_max3_f32 v34, v34, v92, v93
	v_cndmask_b32_e32 v96, v238, v49, vcc
	v_max3_f32 v34, v34, v94, v95
	v_max3_f32 v34, v34, v96, v97
	v_mov_b32_e32 v35, v34
	s_nop 1
	v_permlane32_swap_b32_e32 v34, v35
	v_max_f32_e32 v35, v35, v35
	v_max_f32_e32 v34, v34, v34
	v_max_f32_e32 v34, v34, v35
	v_cmp_gt_f32_e32 vcc, v34, v0
	v_mov_b32_e32 v162, v195
	s_nop 0
	v_cndmask_b32_e32 v194, v231, v34, vcc
	s_cbranch_vccz .LBB0_670
	v_sub_f32_e32 v34, v231, v194
	v_exp_f32_e32 v34, v34
	s_nop 0
	v_mul_f32_e32 v162, v195, v34
	v_pk_mul_f32 v[32:33], v[32:33], v[34:35] op_sel_hi:[1,0]
	v_pk_mul_f32 v[30:31], v[30:31], v[34:35] op_sel_hi:[1,0]
	v_pk_mul_f32 v[28:29], v[28:29], v[34:35] op_sel_hi:[1,0]
	v_pk_mul_f32 v[26:27], v[26:27], v[34:35] op_sel_hi:[1,0]
	v_pk_mul_f32 v[24:25], v[24:25], v[34:35] op_sel_hi:[1,0]
	v_pk_mul_f32 v[22:23], v[22:23], v[34:35] op_sel_hi:[1,0]
	v_pk_mul_f32 v[20:21], v[20:21], v[34:35] op_sel_hi:[1,0]
	v_pk_mul_f32 v[16:17], v[16:17], v[34:35] op_sel_hi:[1,0]
	v_pk_mul_f32 v[14:15], v[14:15], v[34:35] op_sel_hi:[1,0]
	v_pk_mul_f32 v[12:13], v[12:13], v[34:35] op_sel_hi:[1,0]
	v_pk_mul_f32 v[10:11], v[10:11], v[34:35] op_sel_hi:[1,0]
	v_pk_mul_f32 v[8:9], v[8:9], v[34:35] op_sel_hi:[1,0]
	v_pk_mul_f32 v[6:7], v[6:7], v[34:35] op_sel_hi:[1,0]
	v_pk_mul_f32 v[4:5], v[4:5], v[34:35] op_sel_hi:[1,0]
	v_pk_mul_f32 v[18:19], v[18:19], v[34:35] op_sel_hi:[1,0]
	v_pk_mul_f32 v[2:3], v[2:3], v[34:35] op_sel_hi:[1,0]
